# v059 + window-attention loop: V^T fragment LDS reads issued right after the QK MFMAs (under the softmax VALU) instead of just before the PV MFMAs
# baseline (speedup 1.0000x reference)
; template <int HD, int MODE> ...
;     ...
;         if (active) {
;             const LAS unsigned char* kb = lds + cur * BUF + krd;
;             const LAS unsigned char* vb = lds + cur * BUF + vrd;
;             f32x16 s0, s1;
; #pragma unroll
;             for (int r = 0; r < 16; ++r) { s0[r] = 0.f; s1[r] = 0.f; }
;             if constexpr (HD == 64) {
;                 bf16x8 kf0[HD / 16], kf1[HD / 16];
; #pragma unroll
;                 for (int d0 = 0; d0 < HD / 16; ++d0) { kf0[d0] = *(const LAS bf16x8*)(kb + d0 * 32); kf1[d0] = *(const LAS bf16x8*)(kb + 32 * KROW + d0 * 32); }
;                 __builtin_amdgcn_sched_barrier(0);
;                 __builtin_amdgcn_s_setprio(1);
; #pragma unroll
;                 for (int d0 = 0; d0 < HD / 16; ++d0) { s0 = __builtin_amdgcn_mfma_f32_32x32x16_bf16(kf0[d0], qf[d0], s0, 0, 0, 0); s1 = __builtin_amdgcn_mfma_f32_32x32x16_bf16(kf1[d0], qf[d0], s1, 0, 0, 0); }
;                 __builtin_amdgcn_s_setprio(0);
;             } else {
;             __builtin_amdgcn_s_setprio(1);
; #pragma unroll
;             for (int d0 = 0; d0 < HD / 16; ++d0) {
;                 const bf16x8 k0 = *(const LAS bf16x8*)(kb + d0 * 32);
;                 const bf16x8 k1 = *(const LAS bf16x8*)(kb + 32 * KROW + d0 * 32);
;                 s0 = __builtin_amdgcn_mfma_f32_32x32x16_bf16(k0, qf[d0], s0, 0, 0, 0);
;                 s1 = __builtin_amdgcn_mfma_f32_32x32x16_bf16(k1, qf[d0], s1, 0, 0, 0);
;             }
;             __builtin_amdgcn_s_setprio(0); }
;             if (MODE == 1) {
;                 const LAS float* bl = biasl + (64 * t + 8 * hi - (qlo + r32) + 384);
; #pragma unroll
;                 for (int r = 0; r < 16; ++r) { s0[r] += bl[16 * (r >> 3) + (r & 7)]; s1[r] += bl[32 + 16 * (r >> 3) + (r & 7)]; }
;             }
;             float mx = fmaxf(s0[0], s1[0]);
; #pragma unroll
;             for (int r = 1; r < 16; ++r) mx = fmaxf(mx, fmaxf(s0[r], s1[r]));
;             { auto rr = __builtin_amdgcn_permlane32_swap(__float_as_uint(mx), __float_as_uint(mx), false, false); mx = fmaxf(__uint_as_float(rr[0]), __uint_as_float(rr[1])); }
;             const float m_new = fmaxf(m_run, mx);
;             const bool grew = __any(m_new > m_run);
;             const float alpha = __builtin_amdgcn_exp2f(m_run - m_new);
;             m_run = m_new;
;             float rs = 0.f;
; #pragma unroll
.LBB0_520:
	s_add_i32 s29, s6, 63
	s_cmp_ge_i32 s29, s10
	s_cselect_b64 s[46:47], -1, 0
	s_cmp_le_i32 s6, s11
	s_cselect_b64 s[48:49], -1, 0
	s_and_b64 s[46:47], s[46:47], s[48:49]
	s_andn2_b64 vcc, exec, s[46:47]
	s_cbranch_vccnz .LBB0_524
	s_mul_i32 s29, s17, 0x4800
	s_add_i32 s29, s29, 0
	v_add3_u32 v38, s29, v95, v0
	ds_read_b128 v[34:37], v38
	ds_read_b128 v[104:107], v38 offset:32
	ds_read_b128 v[50:53], v38 offset:4608
	ds_read_b128 v[108:111], v38 offset:4640
	ds_read_b128 v[112:115], v38 offset:64
	ds_read_b128 v[116:119], v38 offset:96
	ds_read_b128 v[120:123], v38 offset:4672
	ds_read_b128 v[124:127], v38 offset:4704
	s_setprio 1
	s_waitcnt lgkmcnt(7)
	v_mfma_f32_32x32x16_bf16 v[34:49], v[34:37], v[66:69], 0
	s_waitcnt lgkmcnt(5)
	v_mfma_f32_32x32x16_bf16 v[50:65], v[50:53], v[66:69], 0
	v_mfma_f32_32x32x16_bf16 v[34:49], v[104:107], v[70:73], v[34:49]
	s_waitcnt lgkmcnt(4)
	v_mfma_f32_32x32x16_bf16 v[50:65], v[108:111], v[70:73], v[50:65]
	s_waitcnt lgkmcnt(3)
	v_mfma_f32_32x32x16_bf16 v[34:49], v[112:115], v[74:77], v[34:49]
	s_waitcnt lgkmcnt(1)
	v_mfma_f32_32x32x16_bf16 v[50:65], v[120:123], v[74:77], v[50:65]
	ds_read2_b32 v[130:131], v100 offset1:1
	ds_read2_b32 v[132:133], v100 offset0:32 offset1:33
	ds_read2_b32 v[134:135], v100 offset0:2 offset1:3
	ds_read2_b32 v[136:137], v100 offset0:34 offset1:35
	ds_read2_b32 v[138:139], v100 offset0:4 offset1:5
	ds_read2_b32 v[140:141], v100 offset0:36 offset1:37
	ds_read2_b32 v[142:143], v100 offset0:6 offset1:7
	ds_read2_b32 v[144:145], v100 offset0:38 offset1:39
	ds_read2_b32 v[146:147], v100 offset0:16 offset1:17
	ds_read2_b32 v[148:149], v100 offset0:48 offset1:49
	ds_read2_b32 v[150:151], v100 offset0:18 offset1:19
	ds_read2_b32 v[152:153], v100 offset0:50 offset1:51
	ds_read2_b32 v[154:155], v100 offset0:20 offset1:21
	ds_read2_b32 v[156:157], v100 offset0:52 offset1:53
	v_mfma_f32_32x32x16_bf16 v[34:49], v[116:119], v[78:81], v[34:49]
	s_waitcnt lgkmcnt(14)
	v_mfma_f32_32x32x16_bf16 v[50:65], v[124:127], v[78:81], v[50:65]
	ds_read2_b32 v[158:159], v100 offset0:22 offset1:23
	ds_read2_b32 v[160:161], v100 offset0:54 offset1:55
	v_add3_u32 v162, s29, v99, v0
	ds_read_b128 v[164:167], v162 offset:9216
	ds_read_b128 v[168:171], v162 offset:9248
	ds_read_b128 v[172:175], v162 offset:9280
	ds_read_b128 v[176:179], v162 offset:9312
	ds_read_b128 v[180:183], v162 offset:13824
	ds_read_b128 v[184:187], v162 offset:13856
	ds_read_b128 v[188:191], v162 offset:13888
	ds_read_b128 v[192:195], v162 offset:13920
	s_setprio 0
	s_waitcnt lgkmcnt(8)
	s_nop 10
	v_add_f32_e32 v107, v34, v130
	v_add_f32_e32 v106, v35, v131
	v_add_f32_e32 v110, v50, v132
	v_add_f32_e32 v105, v51, v133
	v_add_f32_e32 v103, v36, v134
	v_add_f32_e32 v51, v37, v135
	v_add_f32_e32 v104, v52, v136
	v_add_f32_e32 v50, v53, v137
	v_add_f32_e32 v52, v38, v138
	v_add_f32_e32 v37, v39, v139
	v_add_f32_e32 v53, v54, v140
	v_add_f32_e32 v36, v55, v141
	v_add_f32_e32 v40, v40, v142
	v_add_f32_e32 v111, v41, v143
	v_add_f32_e32 v112, v56, v144
	v_add_f32_e32 v108, v57, v145
	v_add_f32_e32 v109, v42, v146
	v_add_f32_e32 v57, v43, v147
	v_add_f32_e32 v58, v58, v148
	v_add_f32_e32 v56, v59, v149
	v_add_f32_e32 v54, v44, v150
	v_add_f32_e32 v43, v45, v151
	v_add_f32_e32 v42, v61, v153
	v_add_f32_e32 v55, v60, v152
	v_add_f32_e32 v44, v46, v154
	v_add_f32_e32 v39, v47, v155
	v_add_f32_e32 v45, v62, v156
	v_add_f32_e32 v38, v63, v157
	v_add_f32_e32 v41, v48, v158
	v_max_f32_e32 v34, v106, v105
	v_add_f32_e32 v47, v49, v159
	v_max3_f32 v34, v107, v110, v34
	v_max_f32_e32 v35, v103, v104
	v_max_f32_e32 v49, v51, v50
	v_max3_f32 v34, v34, v35, v49
	v_max_f32_e32 v35, v52, v53
	v_max_f32_e32 v49, v37, v36
	v_max3_f32 v34, v34, v35, v49
	v_max_f32_e32 v35, v40, v112
	v_max_f32_e32 v49, v111, v108
	v_max3_f32 v34, v34, v35, v49
	v_max_f32_e32 v35, v109, v58
	v_max_f32_e32 v49, v57, v56
	v_max3_f32 v34, v34, v35, v49
	v_max_f32_e32 v35, v54, v55
	v_max_f32_e32 v49, v43, v42
	v_add_f32_e32 v48, v64, v160
	v_add_f32_e32 v46, v65, v161
	v_max3_f32 v34, v34, v35, v49
	v_max_f32_e32 v35, v44, v45
	v_max_f32_e32 v49, v39, v38
	v_max3_f32 v34, v34, v35, v49
	v_max_f32_e32 v35, v41, v48
	v_max_f32_e32 v49, v47, v46
	v_max3_f32 v34, v34, v35, v49
	v_mov_b32_e32 v35, v34
	s_nop 1
	v_permlane32_swap_b32_e32 v34, v35
	v_max3_f32 v35, v102, v34, v35
	v_sub_f32_e32 v34, v102, v35
	v_exp_f32_e32 v34, v34
	v_cmp_gt_f32_e32 vcc, v35, v102
	s_cbranch_vccz .LBB0_523
	v_pk_mul_f32 v[16:17], v[16:17], v[34:35] op_sel_hi:[1,0]
	v_pk_mul_f32 v[14:15], v[14:15], v[34:35] op_sel_hi:[1,0]
	v_pk_mul_f32 v[12:13], v[12:13], v[34:35] op_sel_hi:[1,0]
	v_pk_mul_f32 v[10:11], v[10:11], v[34:35] op_sel_hi:[1,0]
	v_pk_mul_f32 v[8:9], v[8:9], v[34:35] op_sel_hi:[1,0]
	v_pk_mul_f32 v[6:7], v[6:7], v[34:35] op_sel_hi:[1,0]
	v_pk_mul_f32 v[4:5], v[4:5], v[34:35] op_sel_hi:[1,0]
	v_pk_mul_f32 v[2:3], v[2:3], v[34:35] op_sel_hi:[1,0]
	v_pk_mul_f32 v[32:33], v[32:33], v[34:35] op_sel_hi:[1,0]
	v_pk_mul_f32 v[30:31], v[30:31], v[34:35] op_sel_hi:[1,0]
	v_pk_mul_f32 v[28:29], v[28:29], v[34:35] op_sel_hi:[1,0]
	v_pk_mul_f32 v[26:27], v[26:27], v[34:35] op_sel_hi:[1,0]
	v_pk_mul_f32 v[24:25], v[24:25], v[34:35] op_sel_hi:[1,0]
	v_pk_mul_f32 v[22:23], v[22:23], v[34:35] op_sel_hi:[1,0]
	v_pk_mul_f32 v[20:21], v[20:21], v[34:35] op_sel_hi:[1,0]
	v_pk_mul_f32 v[18:19], v[18:19], v[34:35] op_sel_hi:[1,0]
; template <int HD, int MODE> ...
;     ...
;             const float alpha = __builtin_amdgcn_exp2f(m_run - m_new);
;             m_run = m_new;
;             float rs = 0.f;
; #pragma unroll
;             for (int r = 0; r < 16; ++r) { s0[r] = __builtin_amdgcn_exp2f(s0[r] - m_new); s1[r] = __builtin_amdgcn_exp2f(s1[r] - m_new); rs += s0[r] + s1[r]; }
;             l_run = l_run * alpha + rs;
;             if (grew) {
; #pragma unroll
;                 for (int d0 = 0; d0 < HD / 32; ++d0)
; #pragma unroll
;                     for (int r = 0; r < 16; ++r) o[d0][r] *= alpha;
;             }
;             bf16x8 pf[4];
;             { u32x4 w;
;               w.x = pk2(s0[0], s0[1]); w.y = pk2(s0[2], s0[3]); w.z = pk2(s0[4], s0[5]); w.w = pk2(s0[6], s0[7]); pf[0] = __builtin_bit_cast(bf16x8, w);
;               w.x = pk2(s0[8], s0[9]); w.y = pk2(s0[10], s0[11]); w.z = pk2(s0[12], s0[13]); w.w = pk2(s0[14], s0[15]); pf[1] = __builtin_bit_cast(bf16x8, w);
;               w.x = pk2(s1[0], s1[1]); w.y = pk2(s1[2], s1[3]); w.z = pk2(s1[4], s1[5]); w.w = pk2(s1[6], s1[7]); pf[2] = __builtin_bit_cast(bf16x8, w);
;               w.x = pk2(s1[8], s1[9]); w.y = pk2(s1[10], s1[11]); w.z = pk2(s1[12], s1[13]); w.w = pk2(s1[14], s1[15]); pf[3] = __builtin_bit_cast(bf16x8, w); }
;             if constexpr (HD == 64) {
;                 bf16x8 vfr[HD / 32][4];
; #pragma unroll
;                 for (int d0 = 0; d0 < HD / 32; ++d0)
; #pragma unroll
;                     for (int kk = 0; kk < 4; ++kk) vfr[d0][kk] = *(const LAS bf16x8*)(vb + d0 * 32 * VROW + kk * 32);
;                 __builtin_amdgcn_sched_barrier(0);
;                 __builtin_amdgcn_s_setprio(1);
; #pragma unroll
;                 for (int d0 = 0; d0 < HD / 32; ++d0)
; #pragma unroll
;                     for (int kk = 0; kk < 4; ++kk) o[d0] = __builtin_amdgcn_mfma_f32_32x32x16_bf16(vfr[d0][kk], pf[kk], o[d0], 0, 0, 0);
;                 __builtin_amdgcn_s_setprio(0);
;             } else {
;             __builtin_amdgcn_s_setprio(1);
; #pragma unroll
;             for (int d0 = 0; d0 < HD / 32; ++d0)
; #pragma unroll
;                 for (int kk = 0; kk < 4; ++kk) {
;                     const bf16x8 vf = *(const LAS bf16x8*)(vb + d0 * 32 * VROW + kk * 32);
;                     o[d0] = __builtin_amdgcn_mfma_f32_32x32x16_bf16(vf, pf[kk], o[d0], 0, 0, 0);
;                 }
.LBB0_523:
	v_sub_f32_e32 v49, v107, v35
	v_sub_f32_e32 v59, v110, v35
	v_exp_f32_e32 v49, v49
	v_exp_f32_e32 v59, v59
	v_sub_f32_e32 v61, v106, v35
	v_sub_f32_e32 v62, v105, v35
	v_exp_f32_e32 v61, v61
	v_exp_f32_e32 v62, v62
	v_add_f32_e32 v60, v49, v59
	v_add_f32_e32 v60, 0, v60
	v_sub_f32_e32 v64, v104, v35
	v_add_f32_e32 v63, v61, v62
	v_add_f32_e32 v60, v63, v60
	v_sub_f32_e32 v63, v103, v35
	v_exp_f32_e32 v63, v63
	v_exp_f32_e32 v64, v64
	v_sub_f32_e32 v51, v51, v35
	v_sub_f32_e32 v50, v50, v35
	v_exp_f32_e32 v51, v51
	v_exp_f32_e32 v50, v50
	v_sub_f32_e32 v52, v52, v35
	v_sub_f32_e32 v53, v53, v35
	v_exp_f32_e32 v52, v52
	v_exp_f32_e32 v53, v53
	v_add_f32_e32 v65, v63, v64
	v_add_f32_e32 v60, v65, v60
	v_add_f32_e32 v65, v51, v50
	v_add_f32_e32 v60, v65, v60
	v_add_f32_e32 v65, v52, v53
	v_sub_f32_e32 v37, v37, v35
	v_sub_f32_e32 v36, v36, v35
	v_add_f32_e32 v60, v65, v60
	v_exp_f32_e32 v65, v37
	v_exp_f32_e32 v102, v36
	v_sub_f32_e32 v37, v40, v35
	v_exp_f32_e32 v40, v37
	v_sub_f32_e32 v37, v112, v35
	v_add_f32_e32 v36, v65, v102
	v_add_f32_e32 v36, v36, v60
	v_exp_f32_e32 v60, v37
	s_nop 0
	v_add_f32_e32 v37, v40, v60
	v_add_f32_e32 v36, v37, v36
	v_sub_f32_e32 v37, v111, v35
	v_exp_f32_e32 v103, v37
	v_sub_f32_e32 v37, v108, v35
	v_exp_f32_e32 v104, v37
	s_nop 0
	v_add_f32_e32 v37, v103, v104
	v_add_f32_e32 v36, v37, v36
	v_sub_f32_e32 v37, v109, v35
	v_exp_f32_e32 v105, v37
	v_sub_f32_e32 v37, v58, v35
	v_exp_f32_e32 v58, v37
	s_nop 0
	v_add_f32_e32 v37, v105, v58
	v_add_f32_e32 v36, v37, v36
	v_sub_f32_e32 v37, v57, v35
	v_exp_f32_e32 v57, v37
	v_sub_f32_e32 v37, v56, v35
	v_exp_f32_e32 v56, v37
	s_nop 0
	v_add_f32_e32 v37, v57, v56
	v_add_f32_e32 v36, v37, v36
	v_sub_f32_e32 v37, v54, v35
	v_exp_f32_e32 v54, v37
	v_sub_f32_e32 v37, v55, v35
	v_exp_f32_e32 v55, v37
	s_nop 0
	v_add_f32_e32 v37, v54, v55
	v_add_f32_e32 v36, v37, v36
	v_sub_f32_e32 v37, v43, v35
	v_exp_f32_e32 v43, v37
	v_sub_f32_e32 v37, v42, v35
	v_exp_f32_e32 v106, v37
	s_nop 0
	v_add_f32_e32 v37, v43, v106
	v_add_f32_e32 v36, v37, v36
	v_sub_f32_e32 v37, v44, v35
	v_exp_f32_e32 v42, v37
	v_sub_f32_e32 v37, v45, v35
	v_exp_f32_e32 v107, v37
	s_nop 0
	v_add_f32_e32 v37, v42, v107
	v_add_f32_e32 v36, v37, v36
	v_sub_f32_e32 v37, v39, v35
	v_exp_f32_e32 v44, v37
	v_sub_f32_e32 v37, v38, v35
	v_exp_f32_e32 v108, v37
	v_cvt_pk_bf16_f32 v38, v52, v65
	v_cvt_pk_bf16_f32 v39, v40, v103
	v_cvt_pk_bf16_f32 v40, v105, v57
	v_add_f32_e32 v37, v44, v108
	v_add_f32_e32 v36, v37, v36
	v_sub_f32_e32 v37, v41, v35
	v_exp_f32_e32 v45, v37
	v_sub_f32_e32 v37, v48, v35
	v_exp_f32_e32 v109, v37
	v_cvt_pk_bf16_f32 v41, v54, v43
	v_cvt_pk_bf16_f32 v42, v42, v44
	v_cvt_pk_bf16_f32 v44, v59, v62
	v_add_f32_e32 v37, v45, v109
	v_add_f32_e32 v36, v37, v36
	v_sub_f32_e32 v37, v47, v35
	v_exp_f32_e32 v47, v37
	v_sub_f32_e32 v37, v46, v35
	v_exp_f32_e32 v110, v37
	v_cvt_pk_bf16_f32 v46, v53, v102
	v_cvt_pk_bf16_f32 v43, v45, v47
	v_cvt_pk_bf16_f32 v45, v64, v50
	v_add_f32_e32 v37, v47, v110
	v_add_f32_e32 v122, v37, v36
	v_fmac_f32_e32 v122, v101, v34
	v_cvt_pk_bf16_f32 v36, v49, v61
	v_cvt_pk_bf16_f32 v37, v63, v51
	v_cvt_pk_bf16_f32 v47, v60, v104
	v_cvt_pk_bf16_f32 v48, v58, v56
	v_cvt_pk_bf16_f32 v49, v55, v106
	v_cvt_pk_bf16_f32 v50, v107, v108
	v_cvt_pk_bf16_f32 v51, v109, v110
	s_setprio 1
	s_waitcnt lgkmcnt(0)
	s_nop 1
	v_mfma_f32_32x32x16_bf16 v[18:33], v[164:167], v[36:39], v[18:33]
	v_mfma_f32_32x32x16_bf16 v[2:17], v[180:183], v[36:39], v[2:17]
	v_mfma_f32_32x32x16_bf16 v[18:33], v[168:171], v[40:43], v[18:33]
	v_mfma_f32_32x32x16_bf16 v[2:17], v[184:187], v[40:43], v[2:17]
	v_mfma_f32_32x32x16_bf16 v[18:33], v[172:175], v[44:47], v[18:33]
	v_mfma_f32_32x32x16_bf16 v[2:17], v[188:191], v[44:47], v[2:17]
	v_mfma_f32_32x32x16_bf16 v[18:33], v[176:179], v[48:51], v[18:33]
	v_mfma_f32_32x32x16_bf16 v[2:17], v[192:195], v[48:51], v[2:17]
	s_setprio 0
	v_mov_b32_e32 v101, v122
	s_andn2_b64 vcc, exec, s[8:9]
	s_mov_b64 s[8:9], -1
	s_cbranch_vccz .LBB0_525
	s_branch .LBB0_526
